# stagger odd-L workgroups by 2x s_sleep100 at start of 13 GEMM phases (desync epilogue HBM bursts)
# speedup vs baseline: 1.0021x; 1.0021x over previous
; DI int otid() { int t = threadIdx.x; asm volatile("" : "+v"(t)); return t; }
; #define GL_LOADA(i, kt) { R.a##i = ldg16((const bf16_t*)ar(m0 + lrow + 64 * i, kt) + lkc * 8); \
;                           R.b##i = ldg16(Bt + (size_t)(n0 + lrow + 64 * i) * ldb + (kt) * 64 + lkc * 8); }
; template <bool AF32, class AR>
; DI void gemm_first(GR& R, const AR& ar, const bf16_t* __restrict__ Bt, int ldb, int m0, int n0) {
;   const int tid = otid();
;   const int lrow = tid >> 3, lkc = tid & 7;
;   GL_LOADA(0, 0) GL_LOADA(1, 0) GL_LOADA(2, 0) GL_LOADA(3, 0)
; }
; template <bool AF32>
; DI void phase_inproj_impl(const void* A, int lda, int nk, const bf16_t* Bt, int ntn, int mixer, const Params& P, unsigned char* smem, int L, int G) {
;   bf16_t* big = (bf16_t*)(P.ws + OFF_BIG);
;   float* mstat = (float*)(P.ws + OFF_MSTAT);
;   const float2* cs64 = (const float2*)(P.ws + OFF_CS64);
;   const float2* cs32 = (const float2*)(P.ws + OFF_CS32);
;   const int ntiles = 256 * ntn;
;   const int ldb = nk * 64;
;   GR R;
;   ARowPlain arb{(const bf16_t*)A, lda};
;   const int pw = ntn > 5 ? 5 : ntn;
;   if (L < ntiles) { int mt, nt; panel_tile(L, ntn, pw, mt, nt); gemm_first<false>(R, arb, Bt, ldb, mt * 256, nt * 256); }
.LBB0_237:
	s_or_b64 exec, exec, s[0:1]
	s_add_u32 s80, s72, 0x4f68800
	s_addc_u32 s81, s73, 0
	s_cmpk_lt_i32 s70, 0xa00
	s_cselect_b64 s[0:1], -1, 0
	s_cmpk_gt_i32 s70, 0x9ff
	s_mul_hi_i32 s2, s70, 0x66666667
	s_waitcnt lgkmcnt(0)
	s_barrier
	s_cselect_b32 s99, 1, 0
	s_bitcmp1_b32 s70, 0
	s_cbranch_scc0 .Lstg_skip_0
	s_sleep 100
	s_sleep 100
.Lstg_skip_0:
	s_cmp_lg_u32 s99, 0
	v_writelane_b32 v246, s2, 27
	s_cbranch_scc1 .LBB0_239
	s_mul_hi_i32 s3, s70, 0x66666667
	s_lshr_b32 s2, s3, 31
	s_ashr_i32 s3, s3, 9
	s_add_i32 s2, s3, s2
	s_mul_i32 s3, s2, 0xfffffb00
	s_add_i32 s3, s3, s70
	s_mul_hi_i32 s4, s3, 0x66666667
	s_lshr_b32 s5, s4, 31
	s_ashr_i32 s4, s4, 1
	s_add_i32 s4, s4, s5
	s_sub_i32 s2, s2, s4
	v_mov_b32_e32 v2, v192
	s_mul_i32 s2, s2, 5
	s_add_i32 s2, s2, s3
	v_ashrrev_i32_e32 v4, 3, v2
	v_lshl_add_u32 v0, s4, 8, v4
	v_ashrrev_i32_e32 v1, 31, v0
	v_lshl_add_u32 v4, s2, 8, v4
	v_lshlrev_b64 v[0:1], 11, v[0:1]
	v_lshlrev_b32_e32 v2, 4, v2
	v_ashrrev_i32_e32 v5, 31, v4
	v_lshl_add_u64 v[0:1], s[80:81], 0, v[0:1]
	v_and_b32_e32 v2, 0x70, v2
	v_mov_b32_e32 v3, 0
	v_lshlrev_b64 v[4:5], 11, v[4:5]
	v_lshl_add_u64 v[0:1], v[0:1], 0, v[2:3]
	v_lshl_add_u64 v[4:5], s[72:73], 0, v[4:5]
	s_mov_b32 s2, 0x20000
	v_lshl_add_u64 v[2:3], v[4:5], 0, v[2:3]
	v_add_co_u32_e32 v4, vcc, s2, v0
	global_load_dwordx4 v[140:143], v[0:1], off
	global_load_dwordx4 v[148:151], v[2:3], off
	v_addc_co_u32_e32 v5, vcc, 0, v1, vcc
	v_add_co_u32_e32 v6, vcc, s2, v2
	s_mov_b32 s2, 0x40000
	s_nop 0
	v_addc_co_u32_e32 v7, vcc, 0, v3, vcc
	global_load_dwordx4 v[136:139], v[4:5], off
	global_load_dwordx4 v[152:155], v[6:7], off
	v_add_co_u32_e32 v4, vcc, s2, v0
	s_nop 1
	v_addc_co_u32_e32 v5, vcc, 0, v1, vcc
	v_add_co_u32_e32 v6, vcc, 0x40000, v2
	s_nop 1
	v_addc_co_u32_e32 v7, vcc, 0, v3, vcc
	v_add_co_u32_e32 v0, vcc, 0x60000, v0
	global_load_dwordx4 v[144:147], v[4:5], off
	global_load_dwordx4 v[156:159], v[6:7], off
	v_addc_co_u32_e32 v1, vcc, 0, v1, vcc
	v_add_co_u32_e32 v2, vcc, 0x60000, v2
	s_nop 1
	v_addc_co_u32_e32 v3, vcc, 0, v3, vcc
	global_load_dwordx4 v[128:131], v[0:1], off
	global_load_dwordx4 v[132:135], v[2:3], off

; DI int otid() { int t = threadIdx.x; asm volatile("" : "+v"(t)); return t; }
; template <bool XF32>
; DI void phase_outproj(const Params& P, int layer, const void* xres, const bf16_t* og, unsigned char* smem, int L, int G) {
;   bf16_t* Sb = (bf16_t*)(P.ws + OFF_BIG);
;   float* stats = (float*)(P.ws + OFF_STATS);
;   const bf16_t* Bt = (const bf16_t*)(P.ws + OFF_WOUTT) + (size_t)layer * 1024 * 1024;
;   bf16_t* stg = (bf16_t*)smem;
;   GR R;
;   ARowPlain ar{og, 1024};
;   if (L < 256 * 4) gemm_first<false>(R, ar, Bt, 1024, (L >> 2) * 256, (L & 3) * 256);
;   for (int t = L; t < 256 * 4; t += G) {
;     const int mt = t >> 2, nt = t & 3;
;     const int tid = otid();
;     const int lane = tid & 63, w = tid >> 6, r = lane & 31, h = lane >> 5;
;     const int wm = w >> 2, wn = w & 3;
;     f32x16 acc[4][2]; acc_zero(acc);
;     gemm_loop<false>(acc, R, ar, Bt, 1024, mt * 256, nt * 256, 16, (bf16_t*)smem, true);
;     if (t + G < 256 * 4) gemm_first<false>(R, ar, Bt, 1024, ((t + G) >> 2) * 256, ((t + G) & 3) * 256);
.LBB0_404:
	s_or_b64 exec, exec, s[0:1]
	s_add_u32 s78, s72, 0x4368800
	s_addc_u32 s79, s73, 0
	s_cmpk_lt_i32 s70, 0x400
	s_cselect_b64 s[0:1], -1, 0
	s_cmpk_gt_i32 s70, 0x3ff
	s_waitcnt lgkmcnt(0)
	s_barrier
	s_cselect_b32 s99, 1, 0
	s_bitcmp1_b32 s70, 0
	s_cbranch_scc0 .Lstg_skip_1
	s_sleep 100
	s_sleep 100
.Lstg_skip_1:
	s_cmp_lg_u32 s99, 0
	s_cbranch_scc1 .LBB0_425
	v_readlane_b32 s2, v246, 22
	v_mov_b32_e32 v2, v192
	s_and_b32 s2, s2, 0xffffff00
	s_lshl_b32 s33, s70, 8
	v_ashrrev_i32_e32 v3, 3, v2
	v_add_u32_e32 v0, s2, v3
	s_and_b32 s3, s33, 0x300
	v_ashrrev_i32_e32 v1, 31, v0
	v_lshlrev_b32_e32 v2, 4, v2
	v_lshlrev_b64 v[0:1], 11, v[0:1]
	v_and_b32_e32 v160, 0x70, v2
	v_add_u32_e32 v2, s3, v3
	v_lshl_add_u64 v[0:1], s[94:95], 0, v[0:1]
	v_mov_b32_e32 v161, 0
	v_ashrrev_i32_e32 v3, 31, v2
	v_lshl_add_u64 v[0:1], v[0:1], 0, v[160:161]
	v_lshlrev_b64 v[2:3], 11, v[2:3]
	s_mov_b32 s35, 0x20000
	v_lshl_add_u64 v[2:3], s[24:25], 0, v[2:3]
	v_add_co_u32_e32 v4, vcc, s35, v0
	v_lshl_add_u64 v[2:3], v[2:3], 0, v[160:161]
	s_nop 0
	v_addc_co_u32_e32 v5, vcc, 0, v1, vcc
	global_load_dwordx4 v[136:139], v[4:5], off
	v_add_co_u32_e32 v4, vcc, s35, v2
	s_mov_b32 s2, 0x40000
	s_nop 0
	v_addc_co_u32_e32 v5, vcc, 0, v3, vcc
	global_load_dwordx4 v[140:143], v[4:5], off
	v_add_co_u32_e32 v4, vcc, s2, v0
	global_load_dwordx4 v[128:131], v[0:1], off
	s_nop 0
	v_addc_co_u32_e32 v5, vcc, 0, v1, vcc
	global_load_dwordx4 v[144:147], v[4:5], off
	v_add_co_u32_e32 v4, vcc, s2, v2
	s_mov_b32 s2, 0x60000
	s_nop 0
	v_addc_co_u32_e32 v5, vcc, 0, v3, vcc
	v_add_co_u32_e32 v0, vcc, s2, v0
	global_load_dwordx4 v[132:135], v[2:3], off
	s_nop 0
	v_addc_co_u32_e32 v1, vcc, 0, v1, vcc
	global_load_dwordx4 v[152:155], v[0:1], off
	v_add_co_u32_e32 v0, vcc, s2, v2
	global_load_dwordx4 v[148:151], v[4:5], off
	s_nop 0
	v_addc_co_u32_e32 v1, vcc, 0, v3, vcc
	global_load_dwordx4 v[156:159], v[0:1], off
	s_add_i32 s2, s70, s74
	s_movk_i32 s43, 0xff00
	s_lshl_b32 s44, s2, 6
	s_lshl_b32 s45, s2, 8
	s_lshl_b32 s42, s74, 8
	s_movk_i32 s46, 0x90
	s_mov_b64 s[2:3], 0x20000
	s_mov_b64 s[14:15], 0x40000
	s_mov_b64 s[30:31], 0x60000
	s_mov_b32 s47, 0xfffff80
	s_movk_i32 s48, 0x208
	s_mov_b32 s34, 0x3fd744fd
	v_mbcnt_hi_u32_b32 v166, -1, v193
	s_mov_b32 s49, s70
	s_branch .LBB0_407

; DI int otid() { int t = threadIdx.x; asm volatile("" : "+v"(t)); return t; }
; template <bool LAST>
; DI void phase_gate(const Params& P, int layer, unsigned char* smem, int L, int G) {
;   const bf16_t* Sb = (const bf16_t*)(P.ws + OFF_BIG);
;   const bf16_t* PPb = (const bf16_t*)(P.ws + OFF_BIG) + BG_PP;
;   const float* stats = (const float*)(P.ws + OFF_STATS);
;   const bf16_t* Bg = (const bf16_t*)(P.ws + OFF_PGT) + (size_t)layer * 1024 * 1024;
;   const float* c1 = (const float*)(P.ws + OFF_C1) + layer * 1024;
;   const float* c2 = (const float*)(P.ws + OFF_C2) + layer * 1024;
;   const float* lg = P.ln_g + layer * 1024; const float* lb = P.ln_b + layer * 1024;
;   bf16_t* xb = (bf16_t*)(P.ws + OFF_XB);
;   float* rowA = (float*)(smem + LDS_ROW_OFF); float* rowB = rowA + 256;
;   float* vecL = (float*)(smem + LDS_VEC_OFF);
;   bf16_t* stg = (bf16_t*)smem;
;   GR R;
;   ARowPlain ars{Sb, 1024};
;   for (int t = L; t < 256 * 4; t += G) {
;     const int mt = t >> 2, nt = t & 3;
;     const int tid = otid();
;     const int lane = tid & 63, w = tid >> 6, r = lane & 31, h = lane >> 5;
;     const int wm = w >> 2, wn = w & 3;
;     if (tid < 256) {
;       const f32x4* st = (const f32x4*)(stats + (size_t)(mt * 256 + tid) * 32);
;       float a = 0.f, b2 = 0.f;
; #pragma unroll
;       for (int q = 0; q < 8; ++q) { const f32x4 v = st[q]; a += v.x + v.z; b2 += v.y + v.w; }
;       const float mu = a * (1.f / 1024.f);
;       const float var = b2 * (1.f / 1024.f) - mu * mu;
;       rowA[tid] = mu; rowB[tid] = rsqrtf(fmaxf(var, 0.f) + 1e-5f);
;       vecL[tid] = c1[nt * 256 + tid]; vecL[256 + tid] = c2[nt * 256 + tid]; vecL[512 + tid] = lg[nt * 256 + tid]; vecL[768 + tid] = lb[nt * 256 + tid];
;     }
;     f32x16 accu[4][2]; acc_zero(accu);
;     if (t == L) gemm_first<false>(R, ars, Bg, 1024, mt * 256, nt * 256);
.LBB0_477:
	s_or_b64 exec, exec, s[2:3]
	s_waitcnt lgkmcnt(0)
	v_cndmask_b32_e64 v0, 0, 1, s[0:1]
	s_add_u32 s66, s72, 0x14f68800
	v_cmp_ne_u32_e64 s[2:3], 1, v0
	s_addc_u32 s67, s73, 0
	s_andn2_b64 vcc, exec, s[0:1]
	v_writelane_b32 v246, s2, 30
	s_barrier
	s_cselect_b32 s99, 1, 0
	s_bitcmp1_b32 s70, 0
	s_cbranch_scc0 .Lstg_skip_2
	s_sleep 100
	s_sleep 100
.Lstg_skip_2:
	s_cmp_lg_u32 s99, 0
	s_nop 0
	v_writelane_b32 v246, s3, 31
	s_cbranch_vccnz .LBB0_488
	s_add_i32 s1, s70, s74
	s_lshl_b32 s33, s1, 6
	s_lshl_b32 s34, s1, 8
	s_lshl_b32 s35, s74, 8
	s_mov_b32 s36, 0
	s_movk_i32 s37, 0xff
	s_mov_b32 s0, 0x3a800000
	s_mov_b32 s38, 0x800000
	v_mov_b32_e32 v161, 0
	s_mov_b32 s39, 0x20000
	s_movk_i32 s40, 0x90
	s_mov_b64 s[2:3], 0x20000
	s_mov_b64 s[14:15], 0x40000
	s_mov_b64 s[22:23], 0x60000
	s_mov_b32 s41, 0xfffff80
	s_movk_i32 s42, 0xff00
	s_mov_b32 s43, 0x3fffff80
	s_movk_i32 s44, 0x208
	s_movk_i32 s45, 0xff80
	s_branch .LBB0_480

; template <bool AF32>
; DI void phase_inproj_impl(const void* A, int lda, int nk, const bf16_t* Bt, int ntn, int mixer, const Params& P, unsigned char* smem, int L, int G) {
;   bf16_t* big = (bf16_t*)(P.ws + OFF_BIG);
;   float* mstat = (float*)(P.ws + OFF_MSTAT);
;   const float2* cs64 = (const float2*)(P.ws + OFF_CS64);
;   const float2* cs32 = (const float2*)(P.ws + OFF_CS32);
;   const int ntiles = 256 * ntn;
;   const int ldb = nk * 64;
;   GR R;
;   ARowPlain arb{(const bf16_t*)A, lda};
;   const int pw = ntn > 5 ? 5 : ntn;
;   if (L < ntiles) { int mt, nt; panel_tile(L, ntn, pw, mt, nt); gemm_first<false>(R, arb, Bt, ldb, mt * 256, nt * 256); }
.LBB0_540:
	s_or_b64 exec, exec, s[0:1]
	s_cmpk_lt_i32 s70, 0x700
	s_cselect_b64 s[0:1], -1, 0
	s_cmpk_gt_i32 s70, 0x6ff
	s_waitcnt lgkmcnt(0)
	s_barrier
	s_cselect_b32 s99, 1, 0
	s_bitcmp1_b32 s70, 0
	s_cbranch_scc0 .Lstg_skip_3
	s_sleep 100
	s_sleep 100
.Lstg_skip_3:
	s_cmp_lg_u32 s99, 0
	s_cbranch_scc1 .LBB0_542
	s_mul_hi_i32 s3, s70, 0x66666667
	s_lshr_b32 s2, s3, 31
	s_ashr_i32 s3, s3, 9
	s_add_i32 s2, s3, s2
	s_mul_i32 s3, s2, 5
	s_sub_i32 s10, 7, s3
	s_min_u32 s10, s10, 5
	v_cvt_f32_ubyte0_e32 v0, s10
	v_rcp_iflag_f32_e32 v0, v0
	s_sub_i32 s13, 0, s10
	s_mulk_i32 s2, 0xfb00
	s_add_i32 s2, s2, s70
	v_mul_f32_e32 v0, 0x4f7ffffe, v0
	v_cvt_u32_f32_e32 v0, v0
	s_abs_i32 s12, s2
	s_ashr_i32 s11, s2, 31
	v_mov_b32_e32 v2, v192
	v_readfirstlane_b32 s14, v0
	s_mul_i32 s13, s13, s14
	s_mul_hi_u32 s13, s14, s13
	s_add_i32 s14, s14, s13
	s_mul_hi_u32 s13, s12, s14
	s_mul_i32 s14, s13, s10
	s_sub_i32 s12, s12, s14
	s_add_i32 s14, s13, 1
	s_sub_i32 s15, s12, s10
	s_cmp_ge_u32 s12, s10
	s_cselect_b32 s13, s14, s13
	s_cselect_b32 s12, s15, s12
	s_add_i32 s14, s13, 1
	s_cmp_ge_u32 s12, s10
	s_cselect_b32 s12, s14, s13
	s_xor_b32 s12, s12, s11
	s_sub_i32 s11, s12, s11
	s_mul_i32 s10, s11, s10
	s_add_i32 s2, s2, s3
	s_sub_i32 s2, s2, s10
	v_ashrrev_i32_e32 v4, 3, v2
	v_lshl_add_u32 v0, s11, 8, v4
	v_ashrrev_i32_e32 v1, 31, v0
	v_lshl_add_u32 v4, s2, 8, v4
	v_lshlrev_b64 v[0:1], 11, v[0:1]
	v_lshlrev_b32_e32 v2, 4, v2
	v_ashrrev_i32_e32 v5, 31, v4
	v_lshl_add_u64 v[0:1], s[80:81], 0, v[0:1]
	v_and_b32_e32 v2, 0x70, v2
	v_mov_b32_e32 v3, 0
	v_lshlrev_b64 v[4:5], 11, v[4:5]
	v_lshl_add_u64 v[0:1], v[0:1], 0, v[2:3]
	v_lshl_add_u64 v[4:5], s[28:29], 0, v[4:5]
	s_mov_b32 s2, 0x20000
	v_lshl_add_u64 v[2:3], v[4:5], 0, v[2:3]
	v_add_co_u32_e32 v4, vcc, s2, v0
	global_load_dwordx4 v[140:143], v[0:1], off
	global_load_dwordx4 v[148:151], v[2:3], off
	v_addc_co_u32_e32 v5, vcc, 0, v1, vcc
	v_add_co_u32_e32 v6, vcc, s2, v2
	s_mov_b32 s2, 0x40000
	s_nop 0
	v_addc_co_u32_e32 v7, vcc, 0, v3, vcc
	global_load_dwordx4 v[136:139], v[4:5], off
	global_load_dwordx4 v[152:155], v[6:7], off
	v_add_co_u32_e32 v4, vcc, s2, v0
	s_nop 1
	v_addc_co_u32_e32 v5, vcc, 0, v1, vcc
	v_add_co_u32_e32 v6, vcc, 0x40000, v2
	s_nop 1
	v_addc_co_u32_e32 v7, vcc, 0, v3, vcc
	v_add_co_u32_e32 v0, vcc, 0x60000, v0
	global_load_dwordx4 v[144:147], v[4:5], off
	global_load_dwordx4 v[156:159], v[6:7], off
	v_addc_co_u32_e32 v1, vcc, 0, v1, vcc
	v_add_co_u32_e32 v2, vcc, 0x60000, v2
	s_nop 1
	v_addc_co_u32_e32 v3, vcc, 0, v3, vcc
	global_load_dwordx4 v[128:131], v[0:1], off
	global_load_dwordx4 v[132:135], v[2:3], off

; DI int otid() { int t = threadIdx.x; asm volatile("" : "+v"(t)); return t; }
; DI void phase_mla_up(const Params& P, unsigned char* smem, int L, int G) {
;   bf16_t* big = (bf16_t*)(P.ws + OFF_BIG);
;   const float* mstat = (const float*)(P.ws + OFF_MSTAT);
;   const float2* cs64 = (const float2*)(P.ws + OFF_CS64);
;   const float2* cs32 = (const float2*)(P.ws + OFF_CS32);
;   float* rowA = (float*)(smem + LDS_ROW_OFF);
;   const int nq = 256 * 6, nkv = 256 * 8;
;   for (int t = L; t < nq + nkv; t += G) {
;     const int tid = otid();
;     const bool isq = t < nq;
;     const int tt = isq ? t : t - nq;
;     const int ntn = isq ? 6 : 8;
;     const int mt = tt / ntn, nt = tt - mt * ntn;
;     if (tid < 256) {
.LBB0_632:
	s_or_b64 exec, exec, s[0:1]
	s_cmpk_gt_i32 s70, 0xdff
	s_waitcnt lgkmcnt(0)
	s_barrier
	s_cselect_b32 s99, 1, 0
	s_bitcmp1_b32 s70, 0
	s_cbranch_scc0 .Lstg_skip_4
	s_sleep 100
	s_sleep 100
.Lstg_skip_4:
	s_cmp_lg_u32 s99, 0
	s_cbranch_scc1 .LBB0_717
	s_add_u32 s2, s72, 0xff68800
	s_addc_u32 s3, s73, 0
	s_mov_b64 s[20:21], -1
	s_mov_b32 s23, 0
	s_movk_i32 s33, 0x100
	v_mov_b32_e32 v164, 0x358637bd
	s_mov_b32 s48, 0x2e368800
	s_movk_i32 s49, 0x200
	s_mov_b32 s50, 0x1a368800
	s_waitcnt vmcnt(5)
	v_mov_b32_e32 v137, 0
	s_mov_b32 s51, 0x8000
	s_mov_b32 s52, 0x10000
	s_mov_b32 s53, 0x18000
	s_movk_i32 s54, 0x90
	s_mov_b64 s[24:25], 0x8000
	s_mov_b64 s[28:29], 0x10000
	s_mov_b64 s[30:31], 0x18000
	s_mov_b32 s55, 0xfffff80
	s_mov_b32 s56, 0x9000
	s_movk_i32 s57, 0x300
	s_movk_i32 s58, 0x208
	v_mov_b32_e32 v165, 0x24000
	v_mov_b32_e32 v166, 0x24020
	v_mov_b32_e32 v167, 0x24040
	v_mov_b32_e32 v168, 0x24060
	v_mov_b32_e32 v169, 0x24080
	v_mov_b32_e32 v170, 0x240a0
	v_mov_b32_e32 v171, 0x240c0
	v_mov_b32_e32 v172, 0x240e0
	v_mov_b32_e32 v173, 0x24100
	v_mov_b32_e32 v174, 0x24120
	v_mov_b32_e32 v175, 0x24140
	v_mov_b32_e32 v176, 0x24160
	v_mov_b32_e32 v177, 0x24180
	v_mov_b32_e32 v178, 0x241a0
	v_mov_b32_e32 v179, 0x241c0
	v_mov_b32_e32 v180, 0x241e0
	s_mov_b32 s59, s70
	s_branch .LBB0_636

; DI int otid() { int t = threadIdx.x; asm volatile("" : "+v"(t)); return t; }
; template <bool XF32>
; DI void phase_outproj(const Params& P, int layer, const void* xres, const bf16_t* og, unsigned char* smem, int L, int G) {
;   bf16_t* Sb = (bf16_t*)(P.ws + OFF_BIG);
;   float* stats = (float*)(P.ws + OFF_STATS);
;   const bf16_t* Bt = (const bf16_t*)(P.ws + OFF_WOUTT) + (size_t)layer * 1024 * 1024;
;   bf16_t* stg = (bf16_t*)smem;
;   GR R;
;   ARowPlain ar{og, 1024};
;   if (L < 256 * 4) gemm_first<false>(R, ar, Bt, 1024, (L >> 2) * 256, (L & 3) * 256);
;   for (int t = L; t < 256 * 4; t += G) {
;     const int mt = t >> 2, nt = t & 3;
;     const int tid = otid();
;     const int lane = tid & 63, w = tid >> 6, r = lane & 31, h = lane >> 5;
;     const int wm = w >> 2, wn = w & 3;
;     f32x16 acc[4][2]; acc_zero(acc);
;     gemm_loop<false>(acc, R, ar, Bt, 1024, mt * 256, nt * 256, 16, (bf16_t*)smem, true);
;     if (t + G < 256 * 4) gemm_first<false>(R, ar, Bt, 1024, ((t + G) >> 2) * 256, ((t + G) & 3) * 256);
.LBB0_845:
	s_or_b64 exec, exec, s[0:1]
	v_readlane_b32 s0, v246, 30
	v_readlane_b32 s1, v246, 31
	s_and_b64 vcc, exec, s[0:1]
	s_waitcnt lgkmcnt(0)
	s_barrier
	s_cselect_b32 s99, 1, 0
	s_bitcmp1_b32 s70, 0
	s_cbranch_scc0 .Lstg_skip_5
	s_sleep 100
	s_sleep 100
.Lstg_skip_5:
	s_cmp_lg_u32 s99, 0
	s_cbranch_vccnz .LBB0_866
	s_add_u32 s0, s72, 0x1b60000
	v_readlane_b32 s2, v246, 22
	v_mov_b32_e32 v2, v192
	s_addc_u32 s1, s73, 0
	s_and_b32 s2, s2, 0xffffff00
	s_lshl_b32 s22, s70, 8
	v_ashrrev_i32_e32 v3, 3, v2
	v_add_u32_e32 v0, s2, v3
	s_and_b32 s3, s22, 0x300
	v_ashrrev_i32_e32 v1, 31, v0
	v_lshlrev_b32_e32 v2, 4, v2
	v_lshlrev_b64 v[0:1], 11, v[0:1]
	v_and_b32_e32 v160, 0x70, v2
	v_add_u32_e32 v2, s3, v3
	v_lshl_add_u64 v[0:1], s[94:95], 0, v[0:1]
	v_mov_b32_e32 v161, 0
	v_ashrrev_i32_e32 v3, 31, v2
	v_lshl_add_u64 v[0:1], v[0:1], 0, v[160:161]
	v_lshlrev_b64 v[2:3], 11, v[2:3]
	s_mov_b32 s13, 0x20000
	v_lshl_add_u64 v[2:3], s[0:1], 0, v[2:3]
	v_add_co_u32_e32 v4, vcc, s13, v0
	v_lshl_add_u64 v[2:3], v[2:3], 0, v[160:161]
	s_nop 0
	v_addc_co_u32_e32 v5, vcc, 0, v1, vcc
	global_load_dwordx4 v[136:139], v[4:5], off
	v_add_co_u32_e32 v4, vcc, s13, v2
	s_mov_b32 s2, 0x40000
	s_nop 0
	v_addc_co_u32_e32 v5, vcc, 0, v3, vcc
	global_load_dwordx4 v[140:143], v[4:5], off
	v_add_co_u32_e32 v4, vcc, s2, v0
	global_load_dwordx4 v[128:131], v[0:1], off
	s_nop 0
	v_addc_co_u32_e32 v5, vcc, 0, v1, vcc
	global_load_dwordx4 v[144:147], v[4:5], off
	v_add_co_u32_e32 v4, vcc, s2, v2
	s_mov_b32 s2, 0x60000
	s_nop 0
	v_addc_co_u32_e32 v5, vcc, 0, v3, vcc
	v_add_co_u32_e32 v0, vcc, s2, v0
	global_load_dwordx4 v[132:135], v[2:3], off
	s_nop 0
	v_addc_co_u32_e32 v1, vcc, 0, v1, vcc
	global_load_dwordx4 v[152:155], v[0:1], off
	v_add_co_u32_e32 v0, vcc, s2, v2
	global_load_dwordx4 v[148:151], v[4:5], off
	s_nop 0
	v_addc_co_u32_e32 v1, vcc, 0, v3, vcc
	global_load_dwordx4 v[156:159], v[0:1], off
	s_add_i32 s2, s70, s74
	s_movk_i32 s24, 0xff00
	s_lshl_b32 s25, s2, 6
	s_lshl_b32 s26, s2, 8
	s_lshl_b32 s23, s74, 8
	s_movk_i32 s27, 0x90
	s_mov_b64 s[2:3], 0x20000
	s_mov_b64 s[4:5], 0x40000
	s_mov_b64 s[10:11], 0x60000
	s_mov_b32 s28, 0xfffff80
	s_movk_i32 s29, 0x208
	s_mov_b32 s12, 0x3fd744fd
	v_mbcnt_hi_u32_b32 v166, -1, v193
	s_mov_b32 s30, s70
	s_branch .LBB0_848

; template <bool LAST>
; DI void phase_gate(const Params& P, int layer, unsigned char* smem, int L, int G) {
;   const bf16_t* Sb = (const bf16_t*)(P.ws + OFF_BIG);
;   const bf16_t* PPb = (const bf16_t*)(P.ws + OFF_BIG) + BG_PP;
;   const float* stats = (const float*)(P.ws + OFF_STATS);
;   const bf16_t* Bg = (const bf16_t*)(P.ws + OFF_PGT) + (size_t)layer * 1024 * 1024;
;   const float* c1 = (const float*)(P.ws + OFF_C1) + layer * 1024;
;   const float* c2 = (const float*)(P.ws + OFF_C2) + layer * 1024;
;   const float* lg = P.ln_g + layer * 1024; const float* lb = P.ln_b + layer * 1024;
;   bf16_t* xb = (bf16_t*)(P.ws + OFF_XB);
;   float* rowA = (float*)(smem + LDS_ROW_OFF); float* rowB = rowA + 256;
;   float* vecL = (float*)(smem + LDS_VEC_OFF);
;   bf16_t* stg = (bf16_t*)smem;
;   GR R;
;   ARowPlain ars{Sb, 1024};
;   for (int t = L; t < 256 * 4; t += G) {
.Lstg_skip_6:
	s_cmp_lg_u32 s99, 0
	s_cbranch_vccnz .LBB0_929
	s_add_u32 s0, s72, 0x2360000
	s_addc_u32 s1, s73, 0
	s_add_u32 s2, s72, 0x2b61000
	s_addc_u32 s3, s73, 0
	v_readlane_b32 s36, v246, 1
	s_add_u32 s4, s72, 0x2b65000
	v_readlane_b32 s44, v246, 9
	v_readlane_b32 s45, v246, 10
	s_addc_u32 s5, s73, 0
	v_readlane_b32 s46, v246, 11
	v_readlane_b32 s47, v246, 12
	s_mov_b64 s[12:13], s[44:45]
	s_add_u32 s10, s12, 0x1000
	s_mov_b64 s[14:15], s[46:47]
	s_addc_u32 s11, s13, 0
	s_add_u32 s12, s14, 0x1000
	v_readlane_b32 s37, v246, 2
	v_readlane_b32 s38, v246, 3
	v_readlane_b32 s39, v246, 4
	v_readlane_b32 s40, v246, 5
	v_readlane_b32 s41, v246, 6
	s_addc_u32 s13, s15, 0
	s_add_i32 s15, s70, s74
	s_lshl_b32 s28, s15, 6
	s_lshl_b32 s29, s15, 8
	s_lshl_b32 s30, s74, 8
	s_mov_b32 s31, 0
	s_movk_i32 s33, 0xff
	s_mov_b32 s14, 0x3a800000
	s_mov_b32 s34, 0x800000
	v_mov_b32_e32 v161, 0
	s_mov_b32 s35, 0x20000
	s_movk_i32 s36, 0x90
	s_mov_b64 s[18:19], 0x20000
	s_mov_b64 s[20:21], 0x40000
	s_mov_b64 s[22:23], 0x60000
	s_mov_b32 s37, 0xfffff80
	s_movk_i32 s38, 0xff00
	s_mov_b32 s39, 0x3fffff80
	s_movk_i32 s40, 0x208
	s_movk_i32 s41, 0xff80
	v_readlane_b32 s42, v246, 7
	v_readlane_b32 s43, v246, 8
	v_readlane_b32 s48, v246, 13
	v_readlane_b32 s49, v246, 14
	v_readlane_b32 s50, v246, 15
	v_readlane_b32 s51, v246, 16
	s_branch .LBB0_921

; DI int otid() { int t = threadIdx.x; asm volatile("" : "+v"(t)); return t; }
; #define GL_LOADA(i, kt) { R.a##i = ldg16((const bf16_t*)ar(m0 + lrow + 64 * i, kt) + lkc * 8); \
;                           R.b##i = ldg16(Bt + (size_t)(n0 + lrow + 64 * i) * ldb + (kt) * 64 + lkc * 8); }
; template <bool AF32, class AR>
; DI void gemm_first(GR& R, const AR& ar, const bf16_t* __restrict__ Bt, int ldb, int m0, int n0) {
;   const int tid = otid();
;   const int lrow = tid >> 3, lkc = tid & 7;
;   GL_LOADA(0, 0) GL_LOADA(1, 0) GL_LOADA(2, 0) GL_LOADA(3, 0)
; }
; template <bool AF32>
; DI void phase_inproj_impl(const void* A, int lda, int nk, const bf16_t* Bt, int ntn, int mixer, const Params& P, unsigned char* smem, int L, int G) {
;   bf16_t* big = (bf16_t*)(P.ws + OFF_BIG);
;   float* mstat = (float*)(P.ws + OFF_MSTAT);
;   const float2* cs64 = (const float2*)(P.ws + OFF_CS64);
;   const float2* cs32 = (const float2*)(P.ws + OFF_CS32);
;   const int ntiles = 256 * ntn;
;   const int ldb = nk * 64;
;   GR R;
;   ARowPlain arb{(const bf16_t*)A, lda};
;   const int pw = ntn > 5 ? 5 : ntn;
;   if (L < ntiles) { int mt, nt; panel_tile(L, ntn, pw, mt, nt); gemm_first<false>(R, arb, Bt, ldb, mt * 256, nt * 256); }
.LBB0_981:
	s_or_b64 exec, exec, s[0:1]
	s_cmpk_lt_i32 s70, 0xf00
	s_cselect_b64 s[0:1], -1, 0
	s_cmpk_gt_i32 s70, 0xeff
	s_waitcnt lgkmcnt(0)
	s_barrier
	s_cselect_b32 s99, 1, 0
	s_bitcmp1_b32 s70, 0
	s_cbranch_scc0 .Lstg_skip_7
	s_sleep 100
	s_sleep 100
.Lstg_skip_7:
	s_cmp_lg_u32 s99, 0
	s_cbranch_scc1 .LBB0_983
	s_mul_hi_i32 s3, s70, 0x66666667
	s_lshr_b32 s2, s3, 31
	s_ashr_i32 s3, s3, 9
	s_add_i32 s2, s3, s2
	s_mul_i32 s3, s2, 0xfffffb00
	s_add_i32 s3, s3, s70
	s_mul_hi_i32 s4, s3, 0x66666667
	s_lshr_b32 s5, s4, 31
	s_ashr_i32 s4, s4, 1
	s_add_i32 s4, s4, s5
	s_sub_i32 s2, s2, s4
	v_mov_b32_e32 v2, v192
	s_mul_i32 s2, s2, 5
	s_add_i32 s2, s2, s3
	v_ashrrev_i32_e32 v4, 3, v2
	v_lshl_add_u32 v0, s4, 8, v4
	v_ashrrev_i32_e32 v1, 31, v0
	v_lshl_add_u32 v4, s2, 8, v4
	v_lshlrev_b64 v[0:1], 11, v[0:1]
	v_lshlrev_b32_e32 v2, 4, v2
	v_ashrrev_i32_e32 v5, 31, v4
	v_lshl_add_u64 v[0:1], s[80:81], 0, v[0:1]
	v_and_b32_e32 v2, 0x70, v2
	v_mov_b32_e32 v3, 0
	v_lshlrev_b64 v[4:5], 11, v[4:5]
	v_lshl_add_u64 v[0:1], v[0:1], 0, v[2:3]
	v_lshl_add_u64 v[4:5], s[16:17], 0, v[4:5]
	s_mov_b32 s2, 0x20000
	v_lshl_add_u64 v[2:3], v[4:5], 0, v[2:3]
	v_add_co_u32_e32 v4, vcc, s2, v0
	global_load_dwordx4 v[140:143], v[0:1], off
	global_load_dwordx4 v[148:151], v[2:3], off
	v_addc_co_u32_e32 v5, vcc, 0, v1, vcc
	v_add_co_u32_e32 v6, vcc, s2, v2
	s_mov_b32 s2, 0x40000
	s_nop 0
	v_addc_co_u32_e32 v7, vcc, 0, v3, vcc
	global_load_dwordx4 v[136:139], v[4:5], off
	global_load_dwordx4 v[152:155], v[6:7], off
	v_add_co_u32_e32 v4, vcc, s2, v0
	s_nop 1
	v_addc_co_u32_e32 v5, vcc, 0, v1, vcc
	v_add_co_u32_e32 v6, vcc, 0x40000, v2
	s_nop 1
	v_addc_co_u32_e32 v7, vcc, 0, v3, vcc
	v_add_co_u32_e32 v0, vcc, 0x60000, v0
	global_load_dwordx4 v[144:147], v[4:5], off
	global_load_dwordx4 v[156:159], v[6:7], off
	v_addc_co_u32_e32 v1, vcc, 0, v1, vcc
	v_add_co_u32_e32 v2, vcc, 0x60000, v2
	s_nop 1
	v_addc_co_u32_e32 v3, vcc, 0, v3, vcc
	global_load_dwordx4 v[128:131], v[0:1], off
	global_load_dwordx4 v[132:135], v[2:3], off

; DI int otid() { int t = threadIdx.x; asm volatile("" : "+v"(t)); return t; }
; template <bool XF32>
; DI void phase_outproj(const Params& P, int layer, const void* xres, const bf16_t* og, unsigned char* smem, int L, int G) {
;   bf16_t* Sb = (bf16_t*)(P.ws + OFF_BIG);
;   float* stats = (float*)(P.ws + OFF_STATS);
;   const bf16_t* Bt = (const bf16_t*)(P.ws + OFF_WOUTT) + (size_t)layer * 1024 * 1024;
;   bf16_t* stg = (bf16_t*)smem;
;   GR R;
;   ARowPlain ar{og, 1024};
;   if (L < 256 * 4) gemm_first<false>(R, ar, Bt, 1024, (L >> 2) * 256, (L & 3) * 256);
;   for (int t = L; t < 256 * 4; t += G) {
;     const int mt = t >> 2, nt = t & 3;
;     const int tid = otid();
;     const int lane = tid & 63, w = tid >> 6, r = lane & 31, h = lane >> 5;
;     const int wm = w >> 2, wn = w & 3;
;     f32x16 acc[4][2]; acc_zero(acc);
;     gemm_loop<false>(acc, R, ar, Bt, 1024, mt * 256, nt * 256, 16, (bf16_t*)smem, true);
;     if (t + G < 256 * 4) gemm_first<false>(R, ar, Bt, 1024, ((t + G) >> 2) * 256, ((t + G) & 3) * 256);
.Lstg_skip_8:
	s_cmp_lg_u32 s99, 0
	s_cbranch_vccnz .LBB0_1444
	s_add_u32 s0, s72, 0x1d60000
	v_readlane_b32 s2, v246, 22
	v_mov_b32_e32 v2, v192
	s_addc_u32 s1, s73, 0
	s_and_b32 s2, s2, 0xffffff00
	s_lshl_b32 s16, s70, 8
	v_ashrrev_i32_e32 v3, 3, v2
	v_add_u32_e32 v0, s2, v3
	s_and_b32 s3, s16, 0x300
	v_ashrrev_i32_e32 v1, 31, v0
	v_lshlrev_b32_e32 v2, 4, v2
	v_lshlrev_b64 v[0:1], 11, v[0:1]
	v_and_b32_e32 v160, 0x70, v2
	v_add_u32_e32 v2, s3, v3
	v_lshl_add_u64 v[0:1], s[94:95], 0, v[0:1]
	v_mov_b32_e32 v161, 0
	v_ashrrev_i32_e32 v3, 31, v2
	v_lshl_add_u64 v[0:1], v[0:1], 0, v[160:161]
	v_lshlrev_b64 v[2:3], 11, v[2:3]
	s_mov_b32 s9, 0x20000
	v_lshl_add_u64 v[2:3], s[0:1], 0, v[2:3]
	v_add_co_u32_e32 v4, vcc, s9, v0
	v_lshl_add_u64 v[2:3], v[2:3], 0, v[160:161]
	s_nop 0
	v_addc_co_u32_e32 v5, vcc, 0, v1, vcc
	global_load_dwordx4 v[136:139], v[4:5], off
	v_add_co_u32_e32 v4, vcc, s9, v2
	s_mov_b32 s2, 0x40000
	s_nop 0
	v_addc_co_u32_e32 v5, vcc, 0, v3, vcc
	global_load_dwordx4 v[140:143], v[4:5], off
	v_add_co_u32_e32 v4, vcc, s2, v0
	global_load_dwordx4 v[128:131], v[0:1], off
	s_nop 0
	v_addc_co_u32_e32 v5, vcc, 0, v1, vcc
	global_load_dwordx4 v[144:147], v[4:5], off
	v_add_co_u32_e32 v4, vcc, s2, v2
	s_mov_b32 s2, 0x60000
	s_nop 0
	v_addc_co_u32_e32 v5, vcc, 0, v3, vcc
	v_add_co_u32_e32 v0, vcc, s2, v0
	global_load_dwordx4 v[132:135], v[2:3], off
	s_nop 0
	v_addc_co_u32_e32 v1, vcc, 0, v1, vcc
	global_load_dwordx4 v[152:155], v[0:1], off
	v_add_co_u32_e32 v0, vcc, s2, v2
	global_load_dwordx4 v[148:151], v[4:5], off
	s_nop 0
	v_addc_co_u32_e32 v1, vcc, 0, v3, vcc
	global_load_dwordx4 v[156:159], v[0:1], off
	s_add_i32 s2, s70, s74
	s_movk_i32 s18, 0xff00
	s_lshl_b32 s19, s2, 6
	s_lshl_b32 s20, s2, 8
	s_lshl_b32 s17, s74, 8
	s_movk_i32 s21, 0x90
	s_mov_b64 s[2:3], 0x20000
	s_mov_b64 s[4:5], 0x40000
	s_mov_b64 s[6:7], 0x60000
	s_mov_b32 s22, 0xfffff80
	s_movk_i32 s23, 0x208
	s_mov_b32 s8, 0x3fd744fd
	v_mbcnt_hi_u32_b32 v166, -1, v193
	s_mov_b32 s24, s70
	s_branch .LBB0_1426

; template <bool LAST>
; DI void phase_gate(const Params& P, int layer, unsigned char* smem, int L, int G) {
;   const bf16_t* Sb = (const bf16_t*)(P.ws + OFF_BIG);
;   const bf16_t* PPb = (const bf16_t*)(P.ws + OFF_BIG) + BG_PP;
;   const float* stats = (const float*)(P.ws + OFF_STATS);
;   const bf16_t* Bg = (const bf16_t*)(P.ws + OFF_PGT) + (size_t)layer * 1024 * 1024;
;   const float* c1 = (const float*)(P.ws + OFF_C1) + layer * 1024;
;   const float* c2 = (const float*)(P.ws + OFF_C2) + layer * 1024;
;   const float* lg = P.ln_g + layer * 1024; const float* lb = P.ln_b + layer * 1024;
;   bf16_t* xb = (bf16_t*)(P.ws + OFF_XB);
;   float* rowA = (float*)(smem + LDS_ROW_OFF); float* rowB = rowA + 256;
;   float* vecL = (float*)(smem + LDS_VEC_OFF);
;   bf16_t* stg = (bf16_t*)smem;
;   GR R;
;   ARowPlain ars{Sb, 1024};
;   for (int t = L; t < 256 * 4; t += G) {
.Lstg_skip_9:
	s_cmp_lg_u32 s99, 0
	s_cbranch_vccnz .LBB0_1507
	s_add_u32 s0, s72, 0x2560000
	s_addc_u32 s1, s73, 0
	s_add_u32 s2, s72, 0x2b62000
	s_addc_u32 s3, s73, 0
	v_readlane_b32 s8, v246, 1
	s_add_u32 s4, s72, 0x2b66000
	v_readlane_b32 s9, v246, 2
	v_readlane_b32 s10, v246, 3
	v_readlane_b32 s11, v246, 4
	v_readlane_b32 s16, v246, 9
	v_readlane_b32 s17, v246, 10
	s_addc_u32 s5, s73, 0
	v_readlane_b32 s18, v246, 11
	v_readlane_b32 s19, v246, 12
	s_mov_b64 s[8:9], s[16:17]
	s_add_u32 s6, s8, 0x2000
	s_mov_b64 s[10:11], s[18:19]
	s_addc_u32 s7, s9, 0
	s_add_u32 s8, s10, 0x2000
	v_readlane_b32 s12, v246, 5
	v_readlane_b32 s13, v246, 6
	v_readlane_b32 s14, v246, 7
	v_readlane_b32 s15, v246, 8
	v_readlane_b32 s22, v246, 15
	v_readlane_b32 s23, v246, 16
	s_addc_u32 s9, s11, 0
	s_add_i32 s11, s70, s74
	s_lshl_b32 s22, s11, 6
	s_lshl_b32 s23, s11, 8
	s_lshl_b32 s24, s74, 8
	s_mov_b32 s25, 0
	s_movk_i32 s26, 0xff
	s_mov_b32 s10, 0x3a800000
	s_mov_b32 s27, 0x800000
	v_mov_b32_e32 v161, 0
	s_mov_b32 s28, 0x20000
	s_movk_i32 s29, 0x90
	s_mov_b64 s[12:13], 0x20000
	s_mov_b64 s[14:15], 0x40000
	s_mov_b64 s[16:17], 0x60000
	s_mov_b32 s30, 0xfffff80
	s_movk_i32 s31, 0xff00
	s_mov_b32 s33, 0x3fffff80
	s_movk_i32 s34, 0x208
	s_movk_i32 s35, 0xff80
	v_readlane_b32 s20, v246, 13
	v_readlane_b32 s21, v246, 14
	s_branch .LBB0_1499

; DI int otid() { int t = threadIdx.x; asm volatile("" : "+v"(t)); return t; }
; #define GL_LOADA(i, kt) { R.a##i = ldg16((const bf16_t*)ar(m0 + lrow + 64 * i, kt) + lkc * 8); \
;                           R.b##i = ldg16(Bt + (size_t)(n0 + lrow + 64 * i) * ldb + (kt) * 64 + lkc * 8); }
; template <bool AF32, class AR>
; DI void gemm_first(GR& R, const AR& ar, const bf16_t* __restrict__ Bt, int ldb, int m0, int n0) {
;   const int tid = otid();
;   const int lrow = tid >> 3, lkc = tid & 7;
;   GL_LOADA(0, 0) GL_LOADA(1, 0) GL_LOADA(2, 0) GL_LOADA(3, 0)
; }
; template <bool AF32>
; DI void phase_inproj_impl(const void* A, int lda, int nk, const bf16_t* Bt, int ntn, int mixer, const Params& P, unsigned char* smem, int L, int G) {
;   bf16_t* big = (bf16_t*)(P.ws + OFF_BIG);
;   float* mstat = (float*)(P.ws + OFF_MSTAT);
;   const float2* cs64 = (const float2*)(P.ws + OFF_CS64);
;   const float2* cs32 = (const float2*)(P.ws + OFF_CS32);
;   const int ntiles = 256 * ntn;
;   const int ldb = nk * 64;
;   GR R;
;   ARowPlain arb{(const bf16_t*)A, lda};
;   const int pw = ntn > 5 ? 5 : ntn;
;   if (L < ntiles) { int mt, nt; panel_tile(L, ntn, pw, mt, nt); gemm_first<false>(R, arb, Bt, ldb, mt * 256, nt * 256); }
.LBB0_1559:
	s_or_b64 exec, exec, s[0:1]
	v_readlane_b32 s0, v246, 28
	v_readlane_b32 s1, v246, 29
	s_and_b64 vcc, exec, s[0:1]
	s_waitcnt lgkmcnt(0)
	s_barrier
	s_cselect_b32 s99, 1, 0
	s_bitcmp1_b32 s70, 0
	s_cbranch_scc0 .Lstg_skip_10
	s_sleep 100
	s_sleep 100
.Lstg_skip_10:
	s_cmp_lg_u32 s99, 0
	s_cbranch_vccnz .LBB0_1561
	v_readlane_b32 s1, v246, 27
	s_lshr_b32 s0, s1, 31
	s_ashr_i32 s1, s1, 9
	s_add_i32 s0, s1, s0
	s_mul_i32 s1, s0, 0xfffffb00
	s_add_i32 s1, s1, s70
	s_mul_hi_i32 s2, s1, 0x66666667
	s_lshr_b32 s3, s2, 31
	s_ashr_i32 s2, s2, 1
	s_add_i32 s2, s2, s3
	s_sub_i32 s0, s0, s2
	v_mov_b32_e32 v2, v192
	s_mul_i32 s0, s0, 5
	s_add_i32 s0, s0, s1
	v_ashrrev_i32_e32 v4, 3, v2
	v_lshl_add_u32 v0, s2, 8, v4
	v_ashrrev_i32_e32 v1, 31, v0
	v_lshl_add_u32 v4, s0, 8, v4
	v_lshlrev_b64 v[0:1], 11, v[0:1]
	v_lshlrev_b32_e32 v2, 4, v2
	v_ashrrev_i32_e32 v5, 31, v4
	v_lshl_add_u64 v[0:1], s[80:81], 0, v[0:1]
	v_and_b32_e32 v2, 0x70, v2
	v_mov_b32_e32 v3, 0
	v_lshlrev_b64 v[4:5], 11, v[4:5]
	v_lshl_add_u64 v[0:1], v[0:1], 0, v[2:3]
	v_lshl_add_u64 v[4:5], s[96:97], 0, v[4:5]
	s_mov_b32 s0, 0x20000
	v_lshl_add_u64 v[2:3], v[4:5], 0, v[2:3]
	v_add_co_u32_e32 v4, vcc, s0, v0
	global_load_dwordx4 v[136:139], v[0:1], off
	global_load_dwordx4 v[140:143], v[2:3], off
	v_addc_co_u32_e32 v5, vcc, 0, v1, vcc
	v_add_co_u32_e32 v6, vcc, s0, v2
	s_mov_b32 s0, 0x40000
	s_nop 0
	v_addc_co_u32_e32 v7, vcc, 0, v3, vcc
	global_load_dwordx4 v[132:135], v[4:5], off
	global_load_dwordx4 v[148:151], v[6:7], off
	v_add_co_u32_e32 v4, vcc, s0, v0
	s_nop 1
	v_addc_co_u32_e32 v5, vcc, 0, v1, vcc
	v_add_co_u32_e32 v6, vcc, 0x40000, v2
	s_nop 1
	v_addc_co_u32_e32 v7, vcc, 0, v3, vcc
	v_add_co_u32_e32 v0, vcc, 0x60000, v0
	global_load_dwordx4 v[144:147], v[4:5], off
	global_load_dwordx4 v[156:159], v[6:7], off
	v_addc_co_u32_e32 v1, vcc, 0, v1, vcc
	v_add_co_u32_e32 v2, vcc, 0x60000, v2
	s_nop 1
	v_addc_co_u32_e32 v3, vcc, 0, v3, vcc
	global_load_dwordx4 v[128:131], v[0:1], off
	global_load_dwordx4 v[152:155], v[2:3], off

; DI int otid() { int t = threadIdx.x; asm volatile("" : "+v"(t)); return t; }
; template <bool XF32>
; DI void phase_outproj(const Params& P, int layer, const void* xres, const bf16_t* og, unsigned char* smem, int L, int G) {
;   bf16_t* Sb = (bf16_t*)(P.ws + OFF_BIG);
;   float* stats = (float*)(P.ws + OFF_STATS);
;   const bf16_t* Bt = (const bf16_t*)(P.ws + OFF_WOUTT) + (size_t)layer * 1024 * 1024;
;   bf16_t* stg = (bf16_t*)smem;
;   GR R;
;   ARowPlain ar{og, 1024};
;   if (L < 256 * 4) gemm_first<false>(R, ar, Bt, 1024, (L >> 2) * 256, (L & 3) * 256);
;   for (int t = L; t < 256 * 4; t += G) {
;     const int mt = t >> 2, nt = t & 3;
;     const int tid = otid();
;     const int lane = tid & 63, w = tid >> 6, r = lane & 31, h = lane >> 5;
;     const int wm = w >> 2, wn = w & 3;
;     f32x16 acc[4][2]; acc_zero(acc);
;     gemm_loop<false>(acc, R, ar, Bt, 1024, mt * 256, nt * 256, 16, (bf16_t*)smem, true);
;     if (t + G < 256 * 4) gemm_first<false>(R, ar, Bt, 1024, ((t + G) >> 2) * 256, ((t + G) & 3) * 256);
.Lstg_skip_11:
	s_cmp_lg_u32 s99, 0
	s_cbranch_vccnz .LBB0_1747
	s_add_u32 s0, s72, 0x1f60000
	v_readlane_b32 s2, v246, 22
	v_mov_b32_e32 v2, v192
	s_addc_u32 s1, s73, 0
	s_and_b32 s2, s2, 0xffffff00
	s_lshl_b32 s16, s70, 8
	v_ashrrev_i32_e32 v3, 3, v2
	v_add_u32_e32 v0, s2, v3
	s_and_b32 s3, s16, 0x300
	v_ashrrev_i32_e32 v1, 31, v0
	v_lshlrev_b32_e32 v2, 4, v2
	v_lshlrev_b64 v[0:1], 11, v[0:1]
	v_and_b32_e32 v160, 0x70, v2
	v_add_u32_e32 v2, s3, v3
	v_lshl_add_u64 v[0:1], s[94:95], 0, v[0:1]
	v_mov_b32_e32 v161, 0
	v_ashrrev_i32_e32 v3, 31, v2
	v_lshl_add_u64 v[0:1], v[0:1], 0, v[160:161]
	v_lshlrev_b64 v[2:3], 11, v[2:3]
	s_mov_b32 s9, 0x20000
	v_lshl_add_u64 v[2:3], s[0:1], 0, v[2:3]
	v_add_co_u32_e32 v4, vcc, s9, v0
	v_lshl_add_u64 v[2:3], v[2:3], 0, v[160:161]
	s_nop 0
	v_addc_co_u32_e32 v5, vcc, 0, v1, vcc
	global_load_dwordx4 v[136:139], v[4:5], off
	v_add_co_u32_e32 v4, vcc, s9, v2
	s_mov_b32 s2, 0x40000
	s_nop 0
	v_addc_co_u32_e32 v5, vcc, 0, v3, vcc
	global_load_dwordx4 v[140:143], v[4:5], off
	v_add_co_u32_e32 v4, vcc, s2, v0
	global_load_dwordx4 v[128:131], v[0:1], off
	s_nop 0
	v_addc_co_u32_e32 v5, vcc, 0, v1, vcc
	global_load_dwordx4 v[144:147], v[4:5], off
	v_add_co_u32_e32 v4, vcc, s2, v2
	s_mov_b32 s2, 0x60000
	s_nop 0
	v_addc_co_u32_e32 v5, vcc, 0, v3, vcc
	v_add_co_u32_e32 v0, vcc, s2, v0
	global_load_dwordx4 v[132:135], v[2:3], off
	s_nop 0
	v_addc_co_u32_e32 v1, vcc, 0, v1, vcc
	global_load_dwordx4 v[152:155], v[0:1], off
	v_add_co_u32_e32 v0, vcc, s2, v2
	global_load_dwordx4 v[148:151], v[4:5], off
	s_nop 0
	v_addc_co_u32_e32 v1, vcc, 0, v3, vcc
	global_load_dwordx4 v[156:159], v[0:1], off
	s_add_i32 s2, s70, s74
	s_movk_i32 s18, 0xff00
	s_lshl_b32 s19, s2, 6
	s_lshl_b32 s20, s2, 8
	s_lshl_b32 s17, s74, 8
	s_movk_i32 s21, 0x90
	s_mov_b64 s[2:3], 0x20000
	s_mov_b64 s[4:5], 0x40000
	s_mov_b64 s[6:7], 0x60000
	s_mov_b32 s22, 0xfffff80
	s_movk_i32 s23, 0x208
	s_mov_b32 s8, 0x3fd744fd
	v_mbcnt_hi_u32_b32 v166, -1, v193
	s_mov_b32 s24, s70
	s_branch .LBB0_1729

; template <bool LAST>
; DI void phase_gate(const Params& P, int layer, unsigned char* smem, int L, int G) {
;   const bf16_t* Sb = (const bf16_t*)(P.ws + OFF_BIG);
;   const bf16_t* PPb = (const bf16_t*)(P.ws + OFF_BIG) + BG_PP;
;   const float* stats = (const float*)(P.ws + OFF_STATS);
;   const bf16_t* Bg = (const bf16_t*)(P.ws + OFF_PGT) + (size_t)layer * 1024 * 1024;
;   const float* c1 = (const float*)(P.ws + OFF_C1) + layer * 1024;
;   const float* c2 = (const float*)(P.ws + OFF_C2) + layer * 1024;
;   const float* lg = P.ln_g + layer * 1024; const float* lb = P.ln_b + layer * 1024;
;   bf16_t* xb = (bf16_t*)(P.ws + OFF_XB);
;   float* rowA = (float*)(smem + LDS_ROW_OFF); float* rowB = rowA + 256;
;   float* vecL = (float*)(smem + LDS_VEC_OFF);
;   bf16_t* stg = (bf16_t*)smem;
;   GR R;
;   ARowPlain ars{Sb, 1024};
;   for (int t = L; t < 256 * 4; t += G) {
.Lstg_skip_12:
	s_cmp_lg_u32 s99, 0
	s_cbranch_vccnz .LBB0_1810
	s_add_u32 s0, s72, 0x2760000
	s_addc_u32 s1, s73, 0
	s_add_u32 s2, s72, 0x2b63000
	s_addc_u32 s3, s73, 0
	v_readlane_b32 s8, v246, 1
	s_add_u32 s4, s72, 0x2b67000
	v_readlane_b32 s9, v246, 2
	v_readlane_b32 s10, v246, 3
	v_readlane_b32 s11, v246, 4
	v_readlane_b32 s16, v246, 9
	v_readlane_b32 s17, v246, 10
	s_addc_u32 s5, s73, 0
	v_readlane_b32 s18, v246, 11
	v_readlane_b32 s19, v246, 12
	s_mov_b64 s[8:9], s[16:17]
	s_add_u32 s6, s8, 0x3000
	s_mov_b64 s[10:11], s[18:19]
	s_addc_u32 s7, s9, 0
	s_add_u32 s8, s10, 0x3000
	v_readlane_b32 s12, v246, 5
	v_readlane_b32 s13, v246, 6
	v_readlane_b32 s14, v246, 7
	v_readlane_b32 s15, v246, 8
	v_readlane_b32 s22, v246, 15
	v_readlane_b32 s23, v246, 16
	s_addc_u32 s9, s11, 0
	s_add_i32 s11, s70, s74
	s_lshl_b32 s22, s11, 6
	s_lshl_b32 s23, s11, 8
	s_lshl_b32 s24, s74, 8
	s_mov_b32 s25, 0
	s_movk_i32 s26, 0xff
	s_mov_b32 s10, 0x3a800000
	s_mov_b32 s27, 0x800000
	v_mov_b32_e32 v161, 0
	s_mov_b32 s28, 0x20000
	s_movk_i32 s29, 0x90
	s_mov_b64 s[12:13], 0x20000
	s_mov_b64 s[14:15], 0x40000
	s_mov_b64 s[16:17], 0x60000
	s_mov_b32 s30, 0xfffff80
	s_movk_i32 s31, 0xff00
	s_mov_b32 s33, 0x3fffff80
	s_movk_i32 s34, 0x208
	s_movk_i32 s35, 0xff80
	v_readlane_b32 s20, v246, 13
	v_readlane_b32 s21, v246, 14
	s_branch .LBB0_1802

; __global__ void __launch_bounds__(512, 2) mega_fwd(Params P) {
;   __shared__ __attribute__((aligned(16))) unsigned char smem[LDS_BYTES];
	.amdhsa_kernel _Z8mega_fwd6Params
		.amdhsa_group_segment_fixed_size 153616
		.amdhsa_private_segment_fixed_size 0
		.amdhsa_kernarg_size 456
		.amdhsa_user_sgpr_count 2
		.amdhsa_user_sgpr_dispatch_ptr 0
		.amdhsa_user_sgpr_queue_ptr 0
		.amdhsa_user_sgpr_kernarg_segment_ptr 1
		.amdhsa_user_sgpr_dispatch_id 0
		.amdhsa_user_sgpr_kernarg_preload_length 0
		.amdhsa_user_sgpr_kernarg_preload_offset 0
		.amdhsa_user_sgpr_private_segment_size 0
		.amdhsa_uses_dynamic_stack 0
		.amdhsa_enable_private_segment 0
		.amdhsa_system_sgpr_workgroup_id_x 1
		.amdhsa_system_sgpr_workgroup_id_y 0
		.amdhsa_system_sgpr_workgroup_id_z 0
		.amdhsa_system_sgpr_workgroup_info 0
		.amdhsa_system_vgpr_workitem_id 2
		.amdhsa_next_free_vgpr 247
		.amdhsa_next_free_sgpr 100
		.amdhsa_accum_offset 248
		.amdhsa_reserve_vcc 1
		.amdhsa_float_round_mode_32 0
		.amdhsa_float_round_mode_16_64 0
		.amdhsa_float_denorm_mode_32 3
		.amdhsa_float_denorm_mode_16_64 3
		.amdhsa_dx10_clamp 1
		.amdhsa_ieee_mode 1
		.amdhsa_fp16_overflow 0
		.amdhsa_tg_split 0
		.amdhsa_exception_fp_ieee_invalid_op 0
		.amdhsa_exception_fp_denorm_src 0
		.amdhsa_exception_fp_ieee_div_zero 0
		.amdhsa_exception_fp_ieee_overflow 0
		.amdhsa_exception_fp_ieee_underflow 0
		.amdhsa_exception_fp_ieee_inexact 0
		.amdhsa_exception_int_div_zero 0
	.end_amdhsa_kernel

; __global__ void __launch_bounds__(512, 2) mega_fwd(Params P) {
;   __shared__ __attribute__((aligned(16))) unsigned char smem[LDS_BYTES];
amdhsa.kernels:
  - .agpr_count:     0
    .args:
      - .offset:         0
        .size:           200
        .value_kind:     by_value
      - .offset:         200
        .size:           4
        .value_kind:     hidden_block_count_x
      - .offset:         204
        .size:           4
        .value_kind:     hidden_block_count_y
      - .offset:         208
        .size:           4
        .value_kind:     hidden_block_count_z
      - .offset:         212
        .size:           2
        .value_kind:     hidden_group_size_x
      - .offset:         214
        .size:           2
        .value_kind:     hidden_group_size_y
      - .offset:         216
        .size:           2
        .value_kind:     hidden_group_size_z
      - .offset:         218
        .size:           2
        .value_kind:     hidden_remainder_x
      - .offset:         220
        .size:           2
        .value_kind:     hidden_remainder_y
      - .offset:         222
        .size:           2
        .value_kind:     hidden_remainder_z
      - .offset:         240
        .size:           8
        .value_kind:     hidden_global_offset_x
      - .offset:         248
        .size:           8
        .value_kind:     hidden_global_offset_y
      - .offset:         256
        .size:           8
        .value_kind:     hidden_global_offset_z
      - .offset:         264
        .size:           2
        .value_kind:     hidden_grid_dims
      - .offset:         288
        .size:           8
        .value_kind:     hidden_multigrid_sync_arg
    .group_segment_fixed_size: 153616
    .kernarg_segment_align: 8
    .kernarg_segment_size: 456
    .language:       OpenCL C
    .language_version:
      - 2
      - 0
    .max_flat_workgroup_size: 512
    .name:           _Z8mega_fwd6Params
    .private_segment_fixed_size: 0
    .sgpr_count:     106
    .sgpr_spill_count: 130
    .symbol:         _Z8mega_fwd6Params.kd
    .uniform_work_group_size: 1
    .uses_dynamic_stack: false
    .vgpr_count:     247
    .vgpr_spill_count: 0
    .wavefront_size: 64
